# attention: the always-half-masked last iteration of the two-tile loop gets a single-tile body (no second-tile reads, MFMAs, scores, exps)
# speedup vs baseline: 1.0005x; 1.0005x over previous
.LBB0_413:
	s_cmp_eq_u32 s51, s42
	s_cbranch_scc1 .Lattn_single
	v_bitop3_b32 v64, s45, v142, v189 bitop3:0x36
	v_bitop3_b32 v72, s45, v143, v189 bitop3:0x36
	v_bitop3_b32 v80, s44, v142, v189 bitop3:0x36
	v_bitop3_b32 v88, s44, v143, v189 bitop3:0x36
	v_mad_i32_i24 v68, v64, s18, v122
	v_mad_i32_i24 v76, v72, s18, v122
	v_mad_i32_i24 v84, v80, s18, v122
	v_mad_i32_i24 v92, v88, s18, v122
	ds_read_b128 v[64:67], v68 offset:18496
	ds_read_b128 v[68:71], v68 offset:18432
	ds_read_b128 v[72:75], v76 offset:18496
	ds_read_b128 v[76:79], v76 offset:18432
	ds_read_b128 v[80:83], v84 offset:18496
	ds_read_b128 v[84:87], v84 offset:18432
	ds_read_b128 v[88:91], v92 offset:18496
	ds_read_b128 v[92:95], v92 offset:18432
	s_waitcnt lgkmcnt(0)
	v_mfma_f32_16x16x32_bf16 v[92:95], v[92:95], v[56:59], 0
	v_cmp_gt_u32_e64 s[60:61], s97, v160
	v_cmp_gt_u32_e64 s[62:63], s97, v161
	v_cmp_gt_u32_e64 s[64:65], s97, v162
	v_cmp_gt_u32_e64 s[72:73], s97, v163
	v_mfma_f32_16x16x32_bf16 v[108:111], v[88:91], v[60:63], v[92:95]
	s_cmp_lt_i32 s51, s42
	s_cselect_b32 s101, s97, 0
	s_cselect_b64 s[2:3], -1, 0
	s_cmp_lg_u64 s[2:3], 0
	v_mfma_f32_16x16x32_bf16 v[84:87], v[84:87], v[56:59], 0
	s_addc_u32 s44, s51, 0
	v_mov_b32_e32 v153, v97
	v_mov_b32_e32 v154, v96
	v_cmp_gt_u32_e64 s[74:75], s97, v164
	v_cmp_gt_u32_e64 s[92:93], s97, v165
	v_cmp_gt_u32_e64 s[94:95], s97, v166
	v_cmp_gt_u32_e64 s[98:99], s97, v167
	s_lshl_b32 s52, s44, 5
	s_lshr_b32 s45, s51, 2
	v_pk_mul_f32 v[108:109], v[108:109], v[126:127] op_sel_hi:[1,0]
	v_pk_mul_f32 v[110:111], v[110:111], v[126:127] op_sel_hi:[1,0]
	v_pk_fma_f32 v[108:109], v[160:161], v[128:129], v[108:109] op_sel:[0,1,0] op_sel_hi:[1,1,1] neg_lo:[0,1,0] neg_hi:[0,1,0]
	v_pk_fma_f32 v[110:111], v[162:163], v[128:129], v[110:111] op_sel:[0,1,0] op_sel_hi:[1,1,1] neg_lo:[0,1,0] neg_hi:[0,1,0]
	v_mfma_f32_16x16x32_bf16 v[104:107], v[80:83], v[60:63], v[84:87]
	v_cndmask_b32_e64 v155, v144, v108, s[60:61]
	v_cndmask_b32_e64 v156, v144, v109, s[62:63]
	v_cndmask_b32_e64 v110, v144, v110, s[64:65]
	v_cndmask_b32_e64 v111, v144, v111, s[72:73]
	v_mfma_f32_16x16x32_bf16 v[76:79], v[76:79], v[56:59], 0
	v_max3_f32 v157, v155, s30, v156
	v_max3_f32 v157, v157, v110, v111
	v_pk_add_f32 v[160:161], v[160:161], v[176:177] op_sel_hi:[1,0]
	v_pk_add_f32 v[162:163], v[162:163], v[176:177] op_sel_hi:[1,0]
	v_cmp_gt_u32_e64 s[60:61], s101, v168
	v_cmp_gt_u32_e64 s[62:63], s101, v169
	v_cmp_gt_u32_e64 s[64:65], s101, v170
	v_cmp_gt_u32_e64 s[72:73], s101, v171
	s_xor_b32 s45, s45, s17
	s_lshl_b32 s45, s45, 7
	v_pk_mul_f32 v[104:105], v[104:105], v[126:127] op_sel_hi:[1,0]
	v_pk_mul_f32 v[106:107], v[106:107], v[126:127] op_sel_hi:[1,0]
	v_pk_fma_f32 v[104:105], v[164:165], v[128:129], v[104:105] op_sel:[0,1,0] op_sel_hi:[1,1,1] neg_lo:[0,1,0] neg_hi:[0,1,0]
	v_pk_fma_f32 v[106:107], v[166:167], v[128:129], v[106:107] op_sel:[0,1,0] op_sel_hi:[1,1,1] neg_lo:[0,1,0] neg_hi:[0,1,0]
	v_mfma_f32_16x16x32_bf16 v[100:103], v[72:75], v[60:63], v[76:79]
	v_cndmask_b32_e64 v108, v144, v104, s[74:75]
	v_cndmask_b32_e64 v109, v144, v105, s[92:93]
	v_cndmask_b32_e64 v106, v144, v106, s[94:95]
	v_cndmask_b32_e64 v107, v144, v107, s[98:99]
	v_mfma_f32_16x16x32_bf16 v[68:71], v[68:71], v[56:59], 0
	v_max3_f32 v157, v157, v108, v109
	v_max3_f32 v157, v157, v106, v107
	v_pk_add_f32 v[164:165], v[164:165], v[176:177] op_sel_hi:[1,0]
	v_pk_add_f32 v[166:167], v[166:167], v[176:177] op_sel_hi:[1,0]
	v_cmp_gt_u32_e64 s[74:75], s101, v172
	v_cmp_gt_u32_e64 s[92:93], s101, v173
	v_cmp_gt_u32_e64 s[94:95], s101, v174
	v_cmp_gt_u32_e64 s[98:99], s101, v175
	s_and_b32 s45, s45, 0x80
	s_and_b32 s50, s43, 0x60
	v_pk_mul_f32 v[100:101], v[100:101], v[126:127] op_sel_hi:[1,0]
	v_pk_mul_f32 v[102:103], v[102:103], v[126:127] op_sel_hi:[1,0]
	v_pk_fma_f32 v[100:101], v[168:169], v[128:129], v[100:101] op_sel:[0,1,0] op_sel_hi:[1,1,1] neg_lo:[0,1,0] neg_hi:[0,1,0]
	v_pk_fma_f32 v[102:103], v[170:171], v[128:129], v[102:103] op_sel:[0,1,0] op_sel_hi:[1,1,1] neg_lo:[0,1,0] neg_hi:[0,1,0]
	v_mfma_f32_16x16x32_bf16 v[96:99], v[64:67], v[60:63], v[68:71]
	v_cndmask_b32_e64 v104, v144, v100, s[60:61]
	v_cndmask_b32_e64 v105, v144, v101, s[62:63]
	v_cndmask_b32_e64 v102, v144, v102, s[64:65]
	v_cndmask_b32_e64 v103, v144, v103, s[72:73]
	v_max3_f32 v157, v157, v104, v105
	v_max3_f32 v157, v157, v102, v103
	v_pk_add_f32 v[168:169], v[168:169], v[176:177] op_sel_hi:[1,0]
	v_pk_add_f32 v[170:171], v[170:171], v[176:177] op_sel_hi:[1,0]
	s_or_b32 s45, s45, s50
	s_nop 1
	v_pk_mul_f32 v[96:97], v[96:97], v[126:127] op_sel_hi:[1,0]
	v_pk_mul_f32 v[98:99], v[98:99], v[126:127] op_sel_hi:[1,0]
	v_pk_fma_f32 v[96:97], v[172:173], v[128:129], v[96:97] op_sel:[0,1,0] op_sel_hi:[1,1,1] neg_lo:[0,1,0] neg_hi:[0,1,0]
	v_pk_fma_f32 v[98:99], v[174:175], v[128:129], v[98:99] op_sel:[0,1,0] op_sel_hi:[1,1,1] neg_lo:[0,1,0] neg_hi:[0,1,0]
	v_cndmask_b32_e64 v100, v144, v96, s[74:75]
	v_cndmask_b32_e64 v101, v144, v97, s[92:93]
	v_cndmask_b32_e64 v98, v144, v98, s[94:95]
	v_cndmask_b32_e64 v97, v144, v99, s[98:99]
	v_max3_f32 v157, v157, v100, v101
	v_max3_f32 v96, v157, v98, v97
	v_pk_add_f32 v[172:173], v[172:173], v[176:177] op_sel_hi:[1,0]
	v_pk_add_f32 v[174:175], v[174:175], v[176:177] op_sel_hi:[1,0]
	ds_bpermute_b32 v99, v150, v96
	s_lshr_b32 s50, s44, 2
	s_xor_b32 s50, s50, s17
	v_bitop3_b32 v64, s45, v123, v143 bitop3:0xde
	s_lshl_b32 s50, s50, 7
	s_waitcnt lgkmcnt(0)
	v_max_f32_e32 v99, v99, v99
	v_max_f32_e32 v96, v96, v99
	ds_bpermute_b32 v99, v151, v96
	v_mad_u32_u24 v76, v64, s18, 0
	v_bitop3_b32 v64, s45, v130, v143 bitop3:0xde
	s_and_b32 s50, s50, 0x80
	s_and_b32 s44, s52, 0x60
	s_waitcnt lgkmcnt(0)
	v_max3_f32 v96, v154, v96, v99
	v_sub_f32_e32 v127, v155, v96
	v_exp_f32_e32 v127, v127
	v_sub_f32_e32 v128, v156, v96
	v_exp_f32_e32 v128, v128
	v_sub_f32_e32 v110, v110, v96
	v_mad_u32_u24 v78, v64, s18, 0
	v_exp_f32_e32 v110, v110
	v_sub_f32_e32 v111, v111, v96
	s_or_b32 s44, s50, s44
	v_add_u32_e32 v72, v76, v125
	v_add_u32_e32 v74, v78, v125
	v_add_u32_e32 v76, v76, v131
	v_add_u32_e32 v78, v78, v131
	v_exp_f32_e32 v111, v111
	v_sub_f32_e32 v108, v108, v96
	v_sub_f32_e32 v97, v97, v96
	ds_read_b64_tr_b16 v[70:71], v74 offset:55296
	ds_read_b64_tr_b16 v[66:67], v74 offset:55328
	ds_read_b64_tr_b16 v[68:69], v72 offset:55296
	ds_read_b64_tr_b16 v[64:65], v72 offset:55328
	ds_read_b64_tr_b16 v[72:73], v72 offset:55360
	ds_read_b64_tr_b16 v[74:75], v74 offset:55360
	ds_read_b64_tr_b16 v[76:77], v76 offset:55296
	ds_read_b64_tr_b16 v[78:79], v78 offset:55296
	v_bitop3_b32 v80, s44, v123, v143 bitop3:0xde
	v_exp_f32_e32 v108, v108
	v_sub_f32_e32 v109, v109, v96
	v_exp_f32_e32 v158, v97
	v_add_f32_e32 v97, 0, v127
	v_mad_u32_u24 v92, v80, s18, 0
	v_bitop3_b32 v80, s44, v130, v143 bitop3:0xde
	v_exp_f32_e32 v109, v109
	v_sub_f32_e32 v106, v106, v96
	v_add_f32_e32 v97, v128, v97
	v_mad_u32_u24 v94, v80, s18, 0
	v_exp_f32_e32 v106, v106
	v_sub_f32_e32 v107, v107, v96
	v_sub_f32_e32 v102, v102, v96
	v_add_f32_e32 v97, v110, v97
	v_add_u32_e32 v88, v92, v125
	v_add_u32_e32 v90, v94, v125
	v_add_u32_e32 v92, v92, v131
	v_add_u32_e32 v94, v94, v131
	v_sub_f32_e32 v99, v154, v96
	v_exp_f32_e32 v107, v107
	v_sub_f32_e32 v104, v104, v96
	v_exp_f32_e32 v154, v102
	v_sub_f32_e32 v102, v103, v96
	v_add_f32_e32 v97, v111, v97
	ds_read_b64_tr_b16 v[86:87], v90 offset:55296
	ds_read_b64_tr_b16 v[82:83], v90 offset:55328
	ds_read_b64_tr_b16 v[84:85], v88 offset:55296
	ds_read_b64_tr_b16 v[80:81], v88 offset:55328
	ds_read_b64_tr_b16 v[88:89], v88 offset:55360
	ds_read_b64_tr_b16 v[90:91], v90 offset:55360
	ds_read_b64_tr_b16 v[92:93], v92 offset:55296
	ds_read_b64_tr_b16 v[94:95], v94 offset:55296
	v_exp_f32_e32 v104, v104
	v_sub_f32_e32 v105, v105, v96
	v_exp_f32_e32 v103, v102
	v_exp_f32_e32 v102, v99
	v_add_f32_e32 v97, v108, v97
	s_add_i32 s50, s51, 2
	v_exp_f32_e32 v105, v105
	v_add_f32_e32 v97, v109, v97
	s_min_i32 s44, s50, s42
	v_sub_f32_e32 v100, v100, v96
	v_add_f32_e32 v97, v106, v97
	s_add_i32 s45, s51, 3
	s_lshr_b32 s51, s44, 2
	v_exp_f32_e32 v155, v100
	v_sub_f32_e32 v100, v101, v96
	v_sub_f32_e32 v98, v98, v96
	v_add_f32_e32 v97, v107, v97
	s_xor_b32 s51, s51, s17
	v_exp_f32_e32 v156, v100
	v_exp_f32_e32 v157, v98
	v_pk_mul_f32 v[54:55], v[54:55], v[102:103] op_sel_hi:[1,0]
	v_pk_mul_f32 v[52:53], v[52:53], v[102:103] op_sel_hi:[1,0]
	v_pk_mul_f32 v[50:51], v[50:51], v[102:103] op_sel_hi:[1,0]
	v_pk_mul_f32 v[48:49], v[48:49], v[102:103] op_sel_hi:[1,0]
	v_pk_mul_f32 v[46:47], v[46:47], v[102:103] op_sel_hi:[1,0]
	v_pk_mul_f32 v[44:45], v[44:45], v[102:103] op_sel_hi:[1,0]
	v_pk_mul_f32 v[42:43], v[42:43], v[102:103] op_sel_hi:[1,0]
	v_pk_mul_f32 v[40:41], v[40:41], v[102:103] op_sel_hi:[1,0]
	v_add_f32_e32 v97, v104, v97
	v_cvt_pk_bf16_f32 v98, v127, v128
	v_cvt_pk_bf16_f32 v99, v110, v111
	v_cvt_pk_bf16_f32 v100, v108, v109
	v_cvt_pk_bf16_f32 v101, v106, v107
	s_lshl_b32 s51, s51, 7
	s_lshl_b32 s44, s44, 5
	v_add_f32_e32 v97, v105, v97
	s_waitcnt lgkmcnt(13)
	v_mfma_f32_16x16x32_bf16 v[52:55], v[68:71], v[98:101], v[52:55]
	s_min_i32 s45, s45, s42
	s_and_b32 s51, s51, 0x80
	s_and_b32 s44, s44, 0x60
	s_waitcnt lgkmcnt(12)
	v_mfma_f32_16x16x32_bf16 v[48:51], v[64:67], v[98:101], v[48:51]
	v_add_f32_e32 v97, v154, v97
	s_or_b32 s44, s51, s44
	s_lshr_b32 s51, s45, 2
	s_waitcnt lgkmcnt(10)
	v_mfma_f32_16x16x32_bf16 v[44:47], v[72:75], v[98:101], v[44:47]
	v_add_f32_e32 v97, v103, v97
	s_xor_b32 s51, s51, s17
	v_add_f32_e32 v97, v155, v97
	s_waitcnt lgkmcnt(8)
	v_mfma_f32_16x16x32_bf16 v[40:43], v[76:79], v[98:101], v[40:43]
	v_cvt_pk_bf16_f32 v64, v104, v105
	v_cvt_pk_bf16_f32 v65, v154, v103
	v_cvt_pk_bf16_f32 v66, v155, v156
	v_cvt_pk_bf16_f32 v67, v157, v158
	s_lshl_b32 s51, s51, 7
	s_lshl_b32 s45, s45, 5
	v_add_f32_e32 v97, v156, v97
	s_waitcnt lgkmcnt(5)
	v_mfma_f32_16x16x32_bf16 v[52:55], v[84:87], v[64:67], v[52:55]
	s_and_b32 s51, s51, 0x80
	s_and_b32 s45, s45, 0x60
	v_add_f32_e32 v97, v157, v97
	s_waitcnt lgkmcnt(4)
	v_mfma_f32_16x16x32_bf16 v[48:51], v[80:83], v[64:67], v[48:51]
	s_or_b32 s45, s51, s45
	v_add_f32_e32 v97, v158, v97
	s_add_i32 s43, s43, 64
	s_waitcnt lgkmcnt(2)
	v_mfma_f32_16x16x32_bf16 v[44:47], v[88:91], v[64:67], v[44:47]
	v_fmac_f32_e32 v97, v153, v102
	v_subrev_u32_e32 v152, 64, v152
	s_cmp_gt_i32 s50, s42
	s_waitcnt lgkmcnt(0)
	v_mfma_f32_16x16x32_bf16 v[40:43], v[92:95], v[64:67], v[40:43]
	s_mov_b32 s51, s50
	s_cbranch_scc0 .LBB0_413
	s_mov_b64 s[2:3], 0
	s_branch .LBB0_415
.Lattn_single:
	v_bitop3_b32 v80, s44, v142, v189 bitop3:0x36
	v_bitop3_b32 v88, s44, v143, v189 bitop3:0x36
	v_mad_i32_i24 v84, v80, s18, v122
	v_mad_i32_i24 v92, v88, s18, v122
	ds_read_b128 v[80:83], v84 offset:18496
	ds_read_b128 v[84:87], v84 offset:18432
	ds_read_b128 v[88:91], v92 offset:18496
	ds_read_b128 v[92:95], v92 offset:18432
	v_bitop3_b32 v64, s44, v123, v143 bitop3:0xde
	v_mad_u32_u24 v76, v64, s18, 0
	v_bitop3_b32 v64, s44, v130, v143 bitop3:0xde
	v_mad_u32_u24 v78, v64, s18, 0
	v_add_u32_e32 v72, v76, v125
	v_add_u32_e32 v74, v78, v125
	v_add_u32_e32 v76, v76, v131
	v_add_u32_e32 v78, v78, v131
	ds_read_b64_tr_b16 v[70:71], v74 offset:55296
	ds_read_b64_tr_b16 v[66:67], v74 offset:55328
	ds_read_b64_tr_b16 v[68:69], v72 offset:55296
	ds_read_b64_tr_b16 v[64:65], v72 offset:55328
	ds_read_b64_tr_b16 v[72:73], v72 offset:55360
	ds_read_b64_tr_b16 v[74:75], v74 offset:55360
	ds_read_b64_tr_b16 v[76:77], v76 offset:55296
	ds_read_b64_tr_b16 v[78:79], v78 offset:55296
	s_waitcnt lgkmcnt(8)
	v_mfma_f32_16x16x32_bf16 v[92:95], v[92:95], v[56:59], 0
	v_cmp_gt_u32_e64 s[60:61], s97, v160
	v_cmp_gt_u32_e64 s[62:63], s97, v161
	v_cmp_gt_u32_e64 s[64:65], s97, v162
	v_cmp_gt_u32_e64 s[72:73], s97, v163
	v_mfma_f32_16x16x32_bf16 v[108:111], v[88:91], v[60:63], v[92:95]
	v_mov_b32_e32 v154, v96
	v_cmp_gt_u32_e64 s[74:75], s97, v164
	v_cmp_gt_u32_e64 s[92:93], s97, v165
	v_cmp_gt_u32_e64 s[94:95], s97, v166
	v_cmp_gt_u32_e64 s[98:99], s97, v167
	v_mfma_f32_16x16x32_bf16 v[84:87], v[84:87], v[56:59], 0
	s_add_i32 s43, s43, 64
	s_nop 7
	v_mfma_f32_16x16x32_bf16 v[104:107], v[80:83], v[60:63], v[84:87]
	v_pk_mul_f32 v[108:109], v[108:109], v[126:127] op_sel_hi:[1,0]
	v_pk_mul_f32 v[110:111], v[110:111], v[126:127] op_sel_hi:[1,0]
	v_pk_fma_f32 v[108:109], v[160:161], v[128:129], v[108:109] op_sel:[0,1,0] op_sel_hi:[1,1,1] neg_lo:[0,1,0] neg_hi:[0,1,0]
	v_pk_fma_f32 v[110:111], v[162:163], v[128:129], v[110:111] op_sel:[0,1,0] op_sel_hi:[1,1,1] neg_lo:[0,1,0] neg_hi:[0,1,0]
	v_cndmask_b32_e64 v108, v144, v108, s[60:61]
	v_cndmask_b32_e64 v109, v144, v109, s[62:63]
	v_cndmask_b32_e64 v110, v144, v110, s[64:65]
	v_cndmask_b32_e64 v111, v144, v111, s[72:73]
	v_max3_f32 v157, v108, s30, v109
	v_max3_f32 v157, v157, v110, v111
	s_nop 1
	v_pk_mul_f32 v[104:105], v[104:105], v[126:127] op_sel_hi:[1,0]
	v_pk_mul_f32 v[106:107], v[106:107], v[126:127] op_sel_hi:[1,0]
	v_pk_fma_f32 v[104:105], v[164:165], v[128:129], v[104:105] op_sel:[0,1,0] op_sel_hi:[1,1,1] neg_lo:[0,1,0] neg_hi:[0,1,0]
	v_pk_fma_f32 v[106:107], v[166:167], v[128:129], v[106:107] op_sel:[0,1,0] op_sel_hi:[1,1,1] neg_lo:[0,1,0] neg_hi:[0,1,0]
	v_cndmask_b32_e64 v104, v144, v104, s[74:75]
	v_cndmask_b32_e64 v105, v144, v105, s[92:93]
	v_cndmask_b32_e64 v106, v144, v106, s[94:95]
	v_cndmask_b32_e64 v107, v144, v107, s[98:99]
	v_max3_f32 v157, v157, v104, v105
	v_max3_f32 v157, v157, v106, v107
	ds_bpermute_b32 v156, v150, v157
	s_waitcnt lgkmcnt(0)
	v_max_f32_e32 v156, v156, v156
	v_max_f32_e32 v157, v157, v156
	ds_bpermute_b32 v156, v151, v157
	s_waitcnt lgkmcnt(0)
	v_max3_f32 v96, v154, v157, v156
	v_sub_f32_e32 v155, v154, v96
	v_pk_add_f32 v[108:109], v[108:109], v[96:97] op_sel_hi:[1,0] neg_lo:[0,1] neg_hi:[0,1]
	v_pk_add_f32 v[110:111], v[110:111], v[96:97] op_sel_hi:[1,0] neg_lo:[0,1] neg_hi:[0,1]
	v_exp_f32_e32 v154, v155
	v_pk_add_f32 v[104:105], v[104:105], v[96:97] op_sel_hi:[1,0] neg_lo:[0,1] neg_hi:[0,1]
	v_exp_f32_e32 v108, v108
	v_pk_add_f32 v[106:107], v[106:107], v[96:97] op_sel_hi:[1,0] neg_lo:[0,1] neg_hi:[0,1]
	v_exp_f32_e32 v109, v109
	v_pk_mul_f32 v[54:55], v[54:55], v[154:155] op_sel_hi:[1,0]
	v_exp_f32_e32 v110, v110
	v_pk_mul_f32 v[52:53], v[52:53], v[154:155] op_sel_hi:[1,0]
	v_exp_f32_e32 v111, v111
	v_pk_mul_f32 v[50:51], v[50:51], v[154:155] op_sel_hi:[1,0]
	v_exp_f32_e32 v104, v104
	v_pk_mul_f32 v[48:49], v[48:49], v[154:155] op_sel_hi:[1,0]
	v_exp_f32_e32 v105, v105
	v_pk_mul_f32 v[46:47], v[46:47], v[154:155] op_sel_hi:[1,0]
	v_exp_f32_e32 v106, v106
	v_pk_mul_f32 v[44:45], v[44:45], v[154:155] op_sel_hi:[1,0]
	v_exp_f32_e32 v107, v107
	v_pk_mul_f32 v[42:43], v[42:43], v[154:155] op_sel_hi:[1,0]
	v_pk_mul_f32 v[40:41], v[40:41], v[154:155] op_sel_hi:[1,0]
	v_cvt_pk_bf16_f32 v212, v108, v109
	v_cvt_pk_bf16_f32 v213, v110, v111
	v_cvt_pk_bf16_f32 v214, v104, v105
	v_cvt_pk_bf16_f32 v215, v106, v107
	v_pk_add_f32 v[204:205], v[108:109], v[110:111]
	v_pk_add_f32 v[206:207], v[104:105], v[106:107]
	s_mov_b64 s[2:3], 0
	s_nop 1
	v_mfma_f32_16x16x32_bf16 v[52:55], v[68:71], v[212:215], v[52:55]
	v_pk_add_f32 v[204:205], v[204:205], v[206:207]
	v_mfma_f32_16x16x32_bf16 v[48:51], v[64:67], v[212:215], v[48:51]
	v_add_f32_e32 v204, v204, v205
	v_mfma_f32_16x16x32_bf16 v[44:47], v[72:75], v[212:215], v[44:47]
	v_fma_f32 v97, v97, v154, v204
	v_mfma_f32_16x16x32_bf16 v[40:43], v[76:79], v[212:215], v[40:43]
	s_branch .LBB0_415
